# speedup vs baseline: 1.0119x; 1.0032x over previous
; #define PARAMS_LOCAL KParams PP_ = kparams(); const __attribute__((address_space(4))) Params& P = *PP_;
; __device__ __forceinline__ unsigned xb_ld(unsigned* p)              { return __hip_atomic_load(p, __ATOMIC_RELAXED, __HIP_MEMORY_SCOPE_AGENT); }
; __device__ __forceinline__ unsigned xb_add(unsigned* p, unsigned v) { return __hip_atomic_fetch_add(p, v, __ATOMIC_RELAXED, __HIP_MEMORY_SCOPE_AGENT); }
; __device__ __forceinline__ unsigned xb_xcc_id() { return (unsigned)__builtin_amdgcn_s_getreg((3 << 11) | 20) & 0xFu; }
; #define XB_SPIN(cond, bar) do { unsigned _sp = 0; while (cond) { __builtin_amdgcn_s_sleep(1); \
;     if ((++_sp & 255u) == 0u) { if (xb_ld(&(bar)[XB_TMO])) break; if (_sp > XB_SPIN_CAP) { atomicAdd(&(bar)[XB_TMO], 1u); break; } } } } while (0)
;   unsigned* st = (unsigned*)(smem_raw + LDS_XB);
;   if (threadIdx.x == 0) {
;     PARAMS_LOCAL
;     unsigned* bar = (unsigned*)(P.ws + OFF_BAR);
;     const unsigned x = xb_xcc_id();
;     xb_add(&bar[XB_XCNT(x)], 1u);
;     __threadfence();
;     const unsigned G = gridDim.x * gridDim.y * gridDim.z;
;     const unsigned old = xb_add(&bar[XB_CNT], 1u), gen = old / G;
;     if (old + 1u == (gen + 1u) * G) xb_add(&bar[XB_GEN], 1u); else XB_SPIN(xb_ld(&bar[XB_GEN]) == gen, bar);
.LBB0_5:
	s_or_b64 exec, exec, s[14:15]
	s_waitcnt vmcnt(0)
	s_load_dwordx2 s[14:15], s[0:1], 0xb8
	s_load_dword s20, s[0:1], 0xc0
	s_mov_b64 s[16:17], exec
	v_mbcnt_lo_u32_b32 v1, s16, 0
	s_add_u32 s6, s0, 0xb8
	v_mbcnt_hi_u32_b32 v1, s17, v1
	s_addc_u32 s7, s1, 0
	v_cmp_eq_u32_e32 vcc, 0, v1
	s_and_saveexec_b64 s[18:19], vcc
	s_cbranch_execz .LBB0_7
	s_bcnt1_i32_b64 s16, s[16:17]
	v_mov_b32_e32 v2, 0
	v_mov_b32_e32 v3, s16
	global_atomic_add v2, v2, v3, s[12:13] sc0

; __device__ __forceinline__ unsigned xb_ld(unsigned* p)              { return __hip_atomic_load(p, __ATOMIC_RELAXED, __HIP_MEMORY_SCOPE_AGENT); }
; __device__ __forceinline__ unsigned xb_add(unsigned* p, unsigned v) { return __hip_atomic_fetch_add(p, v, __ATOMIC_RELAXED, __HIP_MEMORY_SCOPE_AGENT); }
; #define XB_SPIN(cond, bar) do { unsigned _sp = 0; while (cond) { __builtin_amdgcn_s_sleep(1); \
;     if ((++_sp & 255u) == 0u) { if (xb_ld(&(bar)[XB_TMO])) break; if (_sp > XB_SPIN_CAP) { atomicAdd(&(bar)[XB_TMO], 1u); break; } } } } while (0)
;     ...
;     if (old + 1u == (gen + 1u) * G) xb_add(&bar[XB_GEN], 1u); else XB_SPIN(xb_ld(&bar[XB_GEN]) == gen, bar);
;     __threadfence();
;     unsigned nx = 0; for (unsigned j = 0; j < 16; ++j) nx += (xb_ld(&bar[XB_XCNT(j)]) > 0u);
;     st[0] = x; st[1] = xb_ld(&bar[XB_XCNT(x)]); st[2] = nx;
;   }
;   __syncthreads();
.LBB0_21:
	s_or_b64 exec, exec, s[12:13]
	v_mov_b32_e32 v1, 0xfc00000
	s_waitcnt vmcnt(0)
	buffer_inv sc1
	global_load_dword v2, v1, s[8:9] offset:1024 sc1
	global_load_dword v3, v1, s[8:9] offset:1280 sc1
	global_load_dword v4, v1, s[8:9] offset:1536 sc1
	global_load_dword v5, v1, s[8:9] offset:1792 sc1
	global_load_dword v6, v1, s[8:9] offset:2048 sc1
	global_load_dword v7, v1, s[8:9] offset:2304 sc1
	global_load_dword v8, v1, s[8:9] offset:2560 sc1
	global_load_dword v9, v1, s[8:9] offset:2816 sc1
	global_load_dword v10, v1, s[8:9] offset:3072 sc1
	global_load_dword v11, v1, s[8:9] offset:3328 sc1
	global_load_dword v12, v1, s[8:9] offset:3584 sc1
	global_load_dword v13, v1, s[8:9] offset:3840 sc1
	v_mov_b32_e32 v1, 0xfc01000
	global_load_dword v14, v1, s[8:9] sc1
	global_load_dword v15, v1, s[8:9] offset:256 sc1
	global_load_dword v16, v1, s[8:9] offset:512 sc1
	s_mov_b32 s12, 0x20800
	v_mov_b32_e32 v19, s3
	s_add_i32 s3, s12, 0x100
	global_load_dword v1, v1, s[8:9] offset:768 sc1
	v_mov_b32_e32 v18, s3
	v_mov_b32_e32 v17, 0
	ds_write_b32 v18, v19
	global_load_dword v17, v17, s[10:11] offset:1024 sc1
	s_mov_b32 s3, 0x20804
	s_addk_i32 s3, 0x100
	v_mov_b32_e32 v18, s3
	v_mov_b64_e32 v[172:173], s[6:7]
	s_waitcnt vmcnt(16)
	v_cmp_ne_u32_e32 vcc, 0, v2
	s_nop 1
	v_cndmask_b32_e64 v2, 0, 1, vcc
	s_waitcnt vmcnt(14)
	v_cmp_ne_u32_e32 vcc, 0, v4
	s_nop 1
	v_cndmask_b32_e64 v4, 0, 1, vcc
	s_waitcnt vmcnt(12)
	v_cmp_ne_u32_e32 vcc, 0, v6
	s_nop 1
	v_cndmask_b32_e64 v6, 0, 1, vcc
	s_waitcnt vmcnt(10)
	v_cmp_ne_u32_e32 vcc, 0, v8
	s_nop 1
	v_cndmask_b32_e64 v8, 0, 1, vcc
	s_waitcnt vmcnt(8)
	v_cmp_ne_u32_e32 vcc, 0, v10
	s_nop 1
	v_cndmask_b32_e64 v10, 0, 1, vcc
	s_waitcnt vmcnt(6)
	v_cmp_ne_u32_e32 vcc, 0, v12
	s_nop 1
	v_cndmask_b32_e64 v12, 0, 1, vcc
	s_waitcnt vmcnt(4)
	v_cmp_ne_u32_e32 vcc, 0, v14
	s_nop 1
	v_cndmask_b32_e64 v14, 0, 1, vcc
	s_waitcnt vmcnt(2)
	v_cmp_ne_u32_e32 vcc, 0, v16
	s_nop 1
	v_cndmask_b32_e64 v16, 0, 1, vcc
	v_cmp_ne_u32_e32 vcc, 0, v3
	s_nop 1
	v_addc_co_u32_e32 v2, vcc, 0, v2, vcc
	v_cmp_ne_u32_e32 vcc, 0, v5
	s_nop 1
	v_addc_co_u32_e32 v2, vcc, v2, v4, vcc
	v_cmp_ne_u32_e32 vcc, 0, v7
	s_nop 1
	v_addc_co_u32_e32 v2, vcc, v2, v6, vcc
	v_cmp_ne_u32_e32 vcc, 0, v9
	s_nop 1
	v_addc_co_u32_e32 v2, vcc, v2, v8, vcc
	v_cmp_ne_u32_e32 vcc, 0, v11
	s_nop 1
	v_addc_co_u32_e32 v2, vcc, v2, v10, vcc
	v_cmp_ne_u32_e32 vcc, 0, v13
	s_nop 1
	v_addc_co_u32_e32 v2, vcc, v2, v12, vcc
	v_cmp_ne_u32_e32 vcc, 0, v15
	s_nop 1
	v_addc_co_u32_e32 v2, vcc, v2, v14, vcc
	s_waitcnt vmcnt(1)
	v_cmp_ne_u32_e32 vcc, 0, v1
	s_nop 1
	v_addc_co_u32_e32 v1, vcc, v2, v16, vcc
	s_waitcnt vmcnt(0)
	ds_write2_b32 v18, v17, v1 offset1:1
